# attention MoBA/MLA loops: per-step K/V tile addresses strength-reduced to running 64-bit pointers (3-5 adds instead of 9-12 shift/adds per step)
# speedup vs baseline: 1.0056x; 1.0022x over previous
; template <int DQ, int TYPE>
; __device__ __forceinline__ void attn_item(PP p, int layer, int b, int h, int qt, char* lds, const int tid_, unsigned* next_ctr, volatile XLAS unsigned* slot) {
;     ...
;     f32x16 O[4];
; #pragma unroll
;     for (int md = 0; md < 4; ++md)
; #pragma unroll
;         for (int i = 0; i < 16; ++i) O[md][i] = 0.f;
;     float m_run = -1e30f, l_run = 0.f;
;     if (TYPE == 2 && kh == 0) { m_run = p->sinks[layer * 8 + h] * LOG2E; l_run = (hh == 0) ? 1.f : 0.f; }
;     constexpr int GK = (DQ == 192) ? 3 : 4, NG = NKS / GK;
;     A_LSTORE(A, 0); __syncthreads();
;     if (kh == 0) __builtin_amdgcn_s_setprio(2);
; #pragma unroll 1
;     for (int j = j_lo; j <= j_hi; ++j) {
;         const int buf = (j - j_lo) & 1;
;         if (j < j_hi) A_GLOAD(A, j + 1);
.LBB0_637:
	s_waitcnt vmcnt(0)
	s_ashr_i32 s54, s88, 8
	s_lshl_b32 s58, s54, 5
	v_or_b32_e32 v2, s58, v154
	v_mov_b32_e32 v18, v1
	v_mov_b32_e32 v19, v1
	v_mov_b32_e32 v32, v1
	v_mov_b32_e32 v33, v1
	v_mul_lo_u32 v162, v2, s84
	s_lshl_b32 s12, s49, 1
	v_mov_b32_e32 v20, v1
	v_mov_b32_e32 v21, v1
	v_mov_b32_e32 v22, v1
	v_mov_b32_e32 v23, v1
	v_mov_b32_e32 v24, v1
	v_mov_b32_e32 v25, v1
	v_mov_b32_e32 v26, v1
	v_mov_b32_e32 v27, v1
	v_mov_b32_e32 v28, v1
	v_mov_b32_e32 v29, v1
	v_mov_b32_e32 v30, v1
	v_mov_b32_e32 v31, v1
	v_mov_b64_e32 v[2:3], v[18:19]
	v_mov_b64_e32 v[64:65], v[32:33]
	v_mov_b64_e32 v[48:49], v[32:33]
	v_mul_u32_u24_e32 v161, 17, v185
	s_lshl_b32 s57, s80, 1
	s_or_b32 s59, s95, 31
	v_and_b32_e32 v244, 7, v154
	v_lshrrev_b32_e32 v245, 3, v154
	v_mad_u32_u24 v244, v244, 18, v245
	v_mul_u32_u24_e32 v163, 0x88, v244
	v_lshlrev_b32_e32 v147, 2, v155
	s_sub_i32 s60, 64, s12
	s_mov_b32 s61, 0
	v_mov_b32_e32 v164, 0
	v_mov_b32_e32 v176, 0xf149f2ca
	s_mov_b32 s62, s58
	v_mov_b64_e32 v[4:5], v[20:21]
	v_mov_b64_e32 v[6:7], v[22:23]
	v_mov_b64_e32 v[8:9], v[24:25]
	v_mov_b64_e32 v[10:11], v[26:27]
	v_mov_b64_e32 v[12:13], v[28:29]
	v_mov_b64_e32 v[14:15], v[30:31]
	v_mov_b64_e32 v[16:17], v[32:33]
	v_mov_b64_e32 v[62:63], v[30:31]
	v_mov_b64_e32 v[60:61], v[28:29]
	v_mov_b64_e32 v[58:59], v[26:27]
	v_mov_b64_e32 v[56:57], v[24:25]
	v_mov_b64_e32 v[54:55], v[22:23]
	v_mov_b64_e32 v[52:53], v[20:21]
	v_mov_b64_e32 v[50:51], v[18:19]
	v_mov_b64_e32 v[46:47], v[30:31]
	v_mov_b64_e32 v[44:45], v[28:29]
	v_mov_b64_e32 v[42:43], v[26:27]
	v_mov_b64_e32 v[40:41], v[24:25]
	v_mov_b64_e32 v[38:39], v[22:23]
	v_mov_b64_e32 v[36:37], v[20:21]
	v_mov_b64_e32 v[34:35], v[18:19]
	s_mov_b32 s98, 0x10000
	s_mov_b32 s99, 0
	v_lshlrev_b64 v[232:233], 10, v[166:167]
	v_lshlrev_b64 v[234:235], 10, v[168:169]
	v_lshlrev_b64 v[236:237], 10, v[170:171]
	v_lshl_add_u64 v[232:233], v[148:149], 0, v[232:233]
	v_lshl_add_u64 v[234:235], v[148:149], 0, v[234:235]
	v_lshl_add_u64 v[236:237], v[150:151], 0, v[236:237]
	v_lshl_add_u64 v[232:233], s[98:99], 0, v[232:233]
	v_lshl_add_u64 v[234:235], s[98:99], 0, v[234:235]
	v_lshl_add_u64 v[236:237], s[98:99], 0, v[236:237]
	s_cmp_le_u32 s61, s57
	s_cselect_b64 s[12:13], -1, 0
	s_cmp_gt_u32 s61, s57
	s_cbranch_scc1 .LBB0_640
	s_branch .LBB0_639

; template <int DQ, int TYPE>
; __device__ __forceinline__ void attn_item(PP p, int layer, int b, int h, int qt, char* lds, const int tid_, unsigned* next_ctr, volatile XLAS unsigned* slot) {
;     ...
;         if (j < j_hi) A_GLOAD(A, j + 1);
.LBB0_639:
	global_load_dwordx4 v[82:85], v[232:233], off
	global_load_dwordx4 v[86:89], v[234:235], off
	global_load_dwordx4 v[106:109], v[236:237], off
	global_load_dwordx4 v[118:121], v[236:237], off offset:1024
	v_lshl_add_u64 v[232:233], s[98:99], 0, v[232:233]
	v_lshl_add_u64 v[234:235], s[98:99], 0, v[234:235]
	v_lshl_add_u64 v[236:237], s[98:99], 0, v[236:237]

; __device__ __forceinline__ bf16_t cvt_bf16(float v) { return (bf16_t)(cvt_pk_bf16(v, 0.f) & 0xffffu); }
; template <int DQ, int TYPE>
; __device__ __forceinline__ void attn_item(PP p, int layer, int b, int h, int qt, char* lds, const int tid_, unsigned* next_ctr, volatile XLAS unsigned* slot) {
;     ...
;             for (int kk = 0; kk < 2; ++kk) {
;                 bf16x8 x1 = qf[8 + kk], x2 = qf[10 + kk], o1, o2;
; #pragma unroll
;                 for (int j = 0; j < 8; ++j) {
;                     const int f = 16 * kk + 8 * hh + j;
;                     const float cs = r64[2 * f], sn = r64[2 * f + 1];
;                     const float a = __uint_as_float(((unsigned)(unsigned short)x1[j]) << 16), bb = __uint_as_float(((unsigned)(unsigned short)x2[j]) << 16);
;                     o1[j] = (short)cvt_bf16(a * cs - bb * sn); o2[j] = (short)cvt_bf16(bb * cs + a * sn);
;                 }
;                 qf[8 + kk] = o1; qf[10 + kk] = o2;
;             }
;     ...
;     f32x16 O[4];
; #pragma unroll
;     for (int md = 0; md < 4; ++md)
; #pragma unroll
;         for (int i = 0; i < 16; ++i) O[md][i] = 0.f;
;     float m_run = -1e30f, l_run = 0.f;
;     if (TYPE == 2 && kh == 0) { m_run = p->sinks[layer * 8 + h] * LOG2E; l_run = (hh == 0) ? 1.f : 0.f; }
.LBB0_661:
	s_ashr_i32 s56, s14, 8
	v_lshl_add_u64 v[190:191], s[12:13], 0, v[0:1]
	s_lshl_b32 s17, s56, 5
	s_mov_b32 s12, 0x5040100
	v_or_b32_e32 v18, s17, v154
	v_perm_b32 v140, v35, v34, s12
	v_mov_b32_e32 v34, v1
	v_mov_b32_e32 v35, v1
	v_mov_b32_e32 v48, v1
	v_mov_b32_e32 v49, v1
	v_mul_lo_u32 v196, v18, s51
	v_perm_b32 v137, v30, v28, s12
	v_perm_b32 v136, v27, v26, s12
	v_perm_b32 v135, v25, v24, s12
	v_perm_b32 v134, v23, v22, s12
	v_perm_b32 v141, v9, v36, s12
	v_perm_b32 v139, v33, v32, s12
	v_perm_b32 v138, v31, v29, s12
	v_perm_b32 v145, v17, v16, s12
	v_perm_b32 v144, v12, v15, s12
	v_perm_b32 v143, v11, v14, s12
	v_perm_b32 v142, v10, v19, s12
	v_perm_b32 v149, v5, v8, s12
	v_perm_b32 v148, v4, v7, s12
	v_perm_b32 v147, v3, v6, s12
	v_perm_b32 v146, v2, v13, s12
	s_lshl_b32 s12, s49, 1
	v_mov_b32_e32 v36, v1
	v_mov_b32_e32 v37, v1
	v_mov_b32_e32 v38, v1
	v_mov_b32_e32 v39, v1
	v_mov_b32_e32 v40, v1
	v_mov_b32_e32 v41, v1
	v_mov_b32_e32 v42, v1
	v_mov_b32_e32 v43, v1
	v_mov_b32_e32 v44, v1
	v_mov_b32_e32 v45, v1
	v_mov_b32_e32 v46, v1
	v_mov_b32_e32 v47, v1
	v_mov_b64_e32 v[64:65], v[48:49]
	v_mov_b64_e32 v[2:3], v[34:35]
	v_mov_b64_e32 v[18:19], v[34:35]
	v_mul_u32_u24_e32 v195, 17, v185
	s_lshl_b32 s16, s80, 1
	s_or_b32 s50, s15, 31
	v_and_b32_e32 v244, 7, v154
	v_lshrrev_b32_e32 v245, 3, v154
	v_mad_u32_u24 v244, v244, 18, v245
	v_mul_u32_u24_e32 v197, 0x88, v244
	v_lshlrev_b32_e32 v187, 2, v155
	s_sub_i32 s49, 64, s12
	s_mov_b32 s51, 0
	v_mov_b32_e32 v199, 0
	v_mov_b32_e32 v205, 0xf149f2ca
	v_lshlrev_b32_e32 v198, 1, v153
	s_mov_b32 s57, s17
	v_mov_b64_e32 v[62:63], v[46:47]
	v_mov_b64_e32 v[60:61], v[44:45]
	v_mov_b64_e32 v[58:59], v[42:43]
	v_mov_b64_e32 v[56:57], v[40:41]
	v_mov_b64_e32 v[54:55], v[38:39]
	v_mov_b64_e32 v[52:53], v[36:37]
	v_mov_b64_e32 v[50:51], v[34:35]
	v_mov_b64_e32 v[4:5], v[36:37]
	v_mov_b64_e32 v[6:7], v[38:39]
	v_mov_b64_e32 v[8:9], v[40:41]
	v_mov_b64_e32 v[10:11], v[42:43]
	v_mov_b64_e32 v[12:13], v[44:45]
	v_mov_b64_e32 v[14:15], v[46:47]
	v_mov_b64_e32 v[16:17], v[48:49]
	v_mov_b64_e32 v[20:21], v[36:37]
	v_mov_b64_e32 v[22:23], v[38:39]
	v_mov_b64_e32 v[24:25], v[40:41]
	v_mov_b64_e32 v[26:27], v[42:43]
	v_mov_b64_e32 v[28:29], v[44:45]
	v_mov_b64_e32 v[30:31], v[46:47]
	v_mov_b64_e32 v[32:33], v[48:49]
	s_mov_b32 s98, 0x20000
	s_mov_b32 s99, 0
	v_lshlrev_b64 v[232:233], 11, v[166:167]
	v_lshlrev_b64 v[234:235], 11, v[168:169]
	v_lshlrev_b64 v[236:237], 11, v[170:171]
	v_lshlrev_b64 v[238:239], 7, v[174:175]
	v_lshl_add_u64 v[232:233], v[176:177], 0, v[232:233]
	v_lshl_add_u64 v[234:235], v[176:177], 0, v[234:235]
	v_lshl_add_u64 v[236:237], v[176:177], 0, v[236:237]
	v_lshl_add_u64 v[238:239], v[190:191], 0, v[238:239]
	v_lshl_add_u64 v[232:233], s[98:99], 0, v[232:233]
	v_lshl_add_u64 v[234:235], s[98:99], 0, v[234:235]
	v_lshl_add_u64 v[236:237], s[98:99], 0, v[236:237]
	v_add_co_u32_e32 v238, vcc, 0x2000, v238
	v_addc_co_u32_e32 v239, vcc, 0, v239, vcc
	s_cmp_le_u32 s51, s16
	s_cselect_b64 s[12:13], -1, 0
	s_cmp_gt_u32 s51, s16
	s_cbranch_scc1 .LBB0_664
	s_branch .LBB0_663

; template <int DQ, int TYPE>
; __device__ __forceinline__ void attn_item(PP p, int layer, int b, int h, int qt, char* lds, const int tid_, unsigned* next_ctr, volatile XLAS unsigned* slot) {
;     ...
;         if (j < j_hi) A_GLOAD(A, j + 1);
.LBB0_663:
	global_load_dwordx4 v[86:89], v[232:233], off
	global_load_dwordx4 v[90:93], v[234:235], off
	global_load_dwordx4 v[118:121], v[238:239], off
	global_load_dwordx4 v[114:117], v[236:237], off offset:256
	global_load_dwordx4 v[122:125], v[236:237], off offset:2304
	v_lshl_add_u64 v[232:233], s[98:99], 0, v[232:233]
	v_lshl_add_u64 v[234:235], s[98:99], 0, v[234:235]
	v_lshl_add_u64 v[236:237], s[98:99], 0, v[236:237]
	v_add_co_u32_e32 v238, vcc, 0x2000, v238
	v_addc_co_u32_e32 v239, vcc, 0, v239, vcc
